# prep pass 3: 16-bit krope loads land in spare registers and are combined after the counted wait, so the two vmcnt(0) that serialised each iteration's input loads are gone
# speedup vs baseline: 1.0062x; 1.0062x over previous
.LBB0_1175:
	v_readlane_b32 s0, v254, 25
	v_readlane_b32 s1, v254, 26
	s_load_dwordx2 s[2:3], s[0:1], 0x118
	v_mov_b32_e32 v73, 0
	s_waitcnt lgkmcnt(0)
	v_lshl_add_u64 v[14:15], s[2:3], 0, v[38:39]
	global_load_dwordx2 v[60:61], v[14:15], off
	v_lshl_add_u64 v[14:15], s[2:3], 0, v[36:37]
	global_load_dword v62, v[14:15], off
	v_mov_b32_e32 v14, 0
	s_and_saveexec_b64 s[14:15], s[4:5]
	s_cbranch_execz .LBB0_1177
	v_lshl_add_u64 v[16:17], s[2:3], 0, v[34:35]
	v_add_co_u32_e32 v16, vcc, 0x5134000, v16
	s_nop 1
	v_addc_co_u32_e32 v17, vcc, 0, v17, vcc
	global_load_ushort v98, v[16:17], off offset:768
	global_load_ushort v99, v[16:17], off offset:784

.LBB0_1181:
	s_or_b64 exec, exec, s[46:47]
	v_add_u32_e32 v50, s20, v70
	v_cmp_gt_i32_e32 vcc, s33, v50
	v_ashrrev_i32_e32 v51, 31, v50
	v_lshlrev_b32_e32 v0, 1, v72
	v_lshlrev_b32_e32 v52, 1, v74
	s_and_saveexec_b64 s[46:47], vcc
	s_cbranch_execz .LBB0_1189
	v_readlane_b32 s0, v254, 35
	v_readlane_b32 s1, v254, 36
	v_mov_b32_e32 v53, v1
	v_mov_b32_e32 v41, 0
	v_mov_b64_e32 v[16:17], s[0:1]
	s_movk_i32 s0, 0x740
	v_mad_i64_i32 v[16:17], s[0:1], v50, s0, v[16:17]
	v_lshl_add_u64 v[42:43], v[16:17], 0, v[0:1]
	v_lshl_add_u64 v[44:45], v[16:17], 0, v[52:53]
	global_load_dwordx2 v[42:43], v[42:43], off
	s_nop 0
	global_load_dword v71, v[44:45], off offset:512
	v_mov_b32_e32 v44, 0
	s_and_saveexec_b64 s[48:49], s[4:5]
	s_cbranch_execz .LBB0_1184
	v_mov_b32_e32 v41, v1
	v_lshl_add_u64 v[16:17], v[16:17], 0, v[40:41]
	global_load_ushort v100, v[16:17], off offset:768
	s_nop 0
	global_load_ushort v101, v[16:17], off offset:784

.LBB0_1189:
	s_or_b64 exec, exec, s[46:47]
	s_mov_b64 s[0:1], 0xb134000
	s_waitcnt vmcnt(2)
	s_and_saveexec_b64 s[98:99], s[4:5]
	v_lshl_or_b32 v73, v99, 16, v98
	v_lshl_or_b32 v41, v101, 16, v100
	s_or_b64 exec, exec, s[98:99]
	v_and_b32_e32 v83, 0xffff0000, v60
	v_and_b32_e32 v65, 0xffff0000, v61
	v_and_b32_e32 v64, s0, v60
	v_lshlrev_b32_e32 v82, 16, v60
	v_mul_f32_e32 v60, v83, v83
	v_lshlrev_b32_e32 v66, 16, v61
	v_mov_b32_e32 v67, v65
	v_pk_fma_f32 v[60:61], v[82:83], v[82:83], v[60:61] op_sel_hi:[1,1,0]
	s_waitcnt vmcnt(1)
	v_lshlrev_b32_e32 v84, 16, v62
	v_and_b32_e32 v85, 0xffff0000, v62
	v_pk_mul_f32 v[64:65], v[64:65], v[64:65]
	v_pk_fma_f32 v[60:61], v[66:67], v[66:67], v[60:61]
	v_pk_mul_f32 v[62:63], v[84:85], v[84:85]
	v_cndmask_b32_e64 v53, v213, v214, s[16:17]
	v_mov_b32_e32 v64, v62
	v_pk_mov_b32 v[60:61], v[62:63], v[60:61] op_sel:[1,0]
	v_lshl_add_u64 v[16:17], v[56:57], 0, s[0:1]
	v_pk_add_f32 v[60:61], v[64:65], v[60:61]
	ds_bpermute_b32 v63, v68, v61
	ds_bpermute_b32 v62, v68, v60
	v_readlane_b32 s0, v254, 29
	v_readlane_b32 s1, v254, 30
	v_readlane_b32 s2, v254, 25
	v_readlane_b32 s3, v254, 26
	s_waitcnt lgkmcnt(0)
	v_pk_add_f32 v[60:61], v[60:61], v[62:63]
	ds_bpermute_b32 v63, v69, v61
	ds_bpermute_b32 v62, v69, v60
	s_load_dwordx2 s[2:3], s[2:3], 0x118
	s_waitcnt lgkmcnt(0)
	v_pk_add_f32 v[60:61], v[60:61], v[62:63]
	ds_bpermute_b32 v63, v75, v61
	ds_bpermute_b32 v62, v75, v60
	s_waitcnt lgkmcnt(0)
	v_pk_add_f32 v[60:61], v[60:61], v[62:63]
	ds_bpermute_b32 v63, v77, v61
	ds_bpermute_b32 v62, v77, v60
	s_waitcnt lgkmcnt(0)
	v_pk_add_f32 v[60:61], v[60:61], v[62:63]
	ds_bpermute_b32 v65, v79, v61
	ds_bpermute_b32 v64, v79, v60
	v_ashrrev_i32_e32 v63, 7, v70
	v_and_b32_e32 v62, v53, v70
	v_and_b32_e32 v53, -2, v63
	v_cndmask_b32_e64 v53, 0, v53, s[16:17]
	s_waitcnt lgkmcnt(0)
	v_pk_add_f32 v[60:61], v[60:61], v[64:65]
	ds_bpermute_b32 v65, v80, v61
	ds_bpermute_b32 v64, v80, v60
	v_add_u32_e32 v86, s0, v53
	s_brev_b32 s0, 60
	s_mov_b32 s1, 0x3b800000
	v_ashrrev_i32_e32 v87, 31, v86
	s_waitcnt lgkmcnt(0)
	v_pk_add_f32 v[60:61], v[60:61], v[64:65]
	v_lshlrev_b64 v[86:87], 8, v[86:87]
	v_pk_fma_f32 v[60:61], v[60:61], s[0:1], v[162:163] op_sel_hi:[1,1,0]
	s_mov_b32 s0, 0x800000
	v_mul_f32_e32 v53, 0x4b800000, v61
	v_cmp_gt_f32_e32 vcc, s0, v61
	v_mov_b32_e32 v63, v1
	v_lshl_add_u64 v[64:65], v[86:87], 0, v[62:63]
	v_cndmask_b32_e32 v53, v61, v53, vcc
	v_rsq_f32_e32 v53, v53
	v_lshl_add_u64 v[86:87], s[2:3], 0, v[30:31]
	v_mul_f32_e32 v61, 0x45800000, v53
	v_cndmask_b32_e32 v78, v53, v61, vcc
	v_mul_f32_e32 v53, 0x4b800000, v60
	v_cmp_gt_f32_e32 vcc, s0, v60
	v_pk_mul_f32 v[82:83], v[78:79], v[82:83] op_sel_hi:[0,1]
	v_pk_mul_f32 v[66:67], v[78:79], v[66:67] op_sel_hi:[0,1]
	v_cndmask_b32_e32 v53, v60, v53, vcc
	v_rsq_f32_e32 v53, v53
	v_pk_mul_f32 v[82:83], v[10:11], v[82:83]
	v_pk_mul_f32 v[66:67], v[12:13], v[66:67]
	v_cvt_pk_bf16_f32 v60, v82, v83
	v_cvt_pk_bf16_f32 v61, v66, v67
	s_waitcnt vmcnt(0)
	global_store_dwordx2 v[86:87], v[60:61], off
	v_mul_f32_e32 v60, 0x45800000, v53
	v_cndmask_b32_e32 v60, v53, v60, vcc
	v_pk_mul_f32 v[60:61], v[60:61], v[84:85] op_sel_hi:[0,1]
	v_pk_mul_f32 v[66:67], v[18:19], v[60:61]
	v_lshl_add_u64 v[60:61], s[2:3], 0, v[28:29]
	v_cvt_pk_bf16_f32 v53, v66, v67
	global_store_dword v[60:61], v53, off
	v_lshlrev_b64 v[60:61], 9, v[64:65]
	s_and_saveexec_b64 s[46:47], s[16:17]
	s_cbranch_execz .LBB0_1191
	v_readlane_b32 s0, v254, 25
	v_readlane_b32 s1, v254, 26
	s_load_dwordx2 s[0:1], s[0:1], 0x110
	v_lshlrev_b32_e32 v82, 2, v74
	v_mov_b32_e32 v83, v1
	s_waitcnt lgkmcnt(0)
	v_lshl_add_u64 v[84:85], s[0:1], 0, v[60:61]
	v_lshl_add_u64 v[82:83], v[84:85], 0, v[82:83]
	v_add_co_u32_e32 v82, vcc, 0x6000000, v82
	s_nop 1
	v_addc_co_u32_e32 v83, vcc, 0, v83, vcc
	global_store_dwordx2 v[82:83], v[66:67], off
